# PLE tile start: the barrier no longer waits for the previous tile's residual-stream stores to drain before the next tile's first A/B loads are issued (loads are waited by count)
# speedup vs baseline: 1.0037x; 1.0030x over previous
; DI unsigned pk2(float lo, float hi) { f32x2 v = {lo, hi}; return __builtin_bit_cast(unsigned, __builtin_convertvector(v, bf16x2_t)); }
; template <bool AF32, int AMODE, bool SWAP>
; DI void mainloop_rs(f32x16 (&acc)[2][2], const void* Abase, int lda, int arow0, int amax, const bf16_t* Bbase, int ldb, int brow0, int nk, int tid) {
;     ...
;     for (int i = 0; i < 4; ++i) { int row = arow0 + lr + 64 * i; row = row < 0 ? 0 : (row > amax ? amax : row); arow[i] = (long)row * lda + lc * 8; }
;     const bf16_t* bp = Bbase + (long)(brow0 + lr) * ldb + lc * 8;
;     auto gload = [&](int kt) {
;         const int ka = (AMODE == 1) ? ((kt >> 1) * 192 + (kt & 1) * 64) : kt * 64;
; #pragma unroll
;         for (int i = 0; i < 4; ++i) {
;             if (!AF32) ra.v[i] = *(const u32x4*)((const bf16_t*)Abase + arow[i] + ka);
;             else { const float* p = (const float*)Abase + arow[i] + ka; ra.v[2 * i] = *(const u32x4*)p; ra.v[2 * i + 1] = *(const u32x4*)(p + 4); }
;         }
; #pragma unroll
;         for (int i = 0; i < 2; ++i) rb[i] = *(const u32x4*)(bp + (long)(64 * i) * ldb + kt * 64);
;     };
;     auto lstore = [&](int s) {
;         char* sb = smem + s * G_STAGE;
; #pragma unroll
;         for (int i = 0; i < 4; ++i) {
;             u32x4 v;
;             if (!AF32) v = ra.v[i];
;             else { const u32x4 a = ra.v[2 * i], b = ra.v[2 * i + 1];
;                 v.x = pk2(__uint_as_float(a.x), __uint_as_float(a.y)); v.y = pk2(__uint_as_float(a.z), __uint_as_float(a.w));
;                 v.z = pk2(__uint_as_float(b.x), __uint_as_float(b.y)); v.w = pk2(__uint_as_float(b.z), __uint_as_float(b.w)); }
;             *(u32x4*)(sb + st_off + i * 8192) = v;
;         }
; #pragma unroll
;         for (int i = 0; i < 2; ++i) *(u32x4*)(sb + G_BOFF + st_off + i * 8192) = rb[i];
;     };
;     __syncthreads();
;     gload(0); lstore(0); __syncthreads();
;     for (int kt = 0; kt < nk; ++kt) {
;         const bool more = kt + 1 < nk;
;         if (more) gload(kt + 1);
;         const char* sb = smem + (kt & 1) * G_STAGE;
; #pragma unroll
;         for (int ks = 0; ks < 4; ++ks) {
;             const int co = (lk ^ (2 * ks)) << 4;
;             bf16x8 a0 = *(const bf16x8*)(sb + a_off + co), a1 = *(const bf16x8*)(sb + a_off + 4096 + co);
;             bf16x8 b0 = *(const bf16x8*)(sb + b_off + co), b1 = *(const bf16x8*)(sb + b_off + 4096 + co);
.LBB0_1905:
	s_ashr_i32 s0, s42, 31
	s_lshr_b32 s0, s0, 29
	s_add_i32 s1, s42, s0
	s_ashr_i32 s0, s1, 3
	s_lshl_b32 s43, s0, 8
	v_add_u32_e32 v0, s43, v158
	v_min_u32_e32 v1, 0x7fff, v0
	s_and_b32 s1, s1, 0x1fffff8
	v_lshlrev_b32_e32 v1, 8, v1
	v_cmp_lt_i32_e32 vcc, -1, v0
	s_sub_i32 s1, s42, s1
	s_lshl_b32 s28, s1, 7
	v_cndmask_b32_e32 v1, 0, v1, vcc
	v_or_b32_e32 v4, v1, v160
	v_min_i32_e32 v1, 0x7fbf, v0
	v_mov_b32_e32 v2, 0x4000
	s_movk_i32 s1, 0xffbf
	v_lshl_add_u32 v1, v1, 8, v2
	v_cmp_lt_i32_e32 vcc, s1, v0
	v_mov_b32_e32 v2, 0x8000
	s_movk_i32 s1, 0xff7f
	v_cndmask_b32_e32 v1, 0, v1, vcc
	v_or_b32_e32 v176, v1, v160
	v_min_i32_e32 v1, 0x7f7f, v0
	v_lshl_add_u32 v1, v1, 8, v2
	v_cmp_lt_i32_e32 vcc, s1, v0
	v_mov_b32_e32 v5, 0xc000
	s_movk_i32 s1, 0xff3f
	v_cndmask_b32_e32 v1, 0, v1, vcc
	v_or_b32_e32 v2, v1, v160
	v_min_i32_e32 v1, 0x7f3f, v0
	v_lshl_add_u32 v1, v1, 8, v5
	v_cmp_lt_i32_e32 vcc, s1, v0
	v_add_u32_e32 v0, s28, v158
	v_mov_b32_e32 v3, v177
	v_cndmask_b32_e32 v5, 0, v1, vcc
	v_ashrrev_i32_e32 v1, 31, v0
	v_lshlrev_b64 v[0:1], 9, v[0:1]
	v_lshl_add_u64 v[0:1], v[144:145], 0, v[0:1]
	s_mov_b32 s1, 0x8000
	v_lshlrev_b32_e32 v62, 2, v4
	v_or_b32_e32 v4, v5, v160
	v_lshl_add_u64 v[8:9], v[176:177], 2, s[26:27]
	v_mov_b32_e32 v5, v177
	v_lshl_add_u64 v[6:7], v[2:3], 2, s[26:27]
	v_add_co_u32_e32 v2, vcc, s1, v0
	s_barrier
	global_load_dwordx4 v[10:13], v[0:1], off
	global_load_dwordx4 v[14:17], v62, s[26:27] offset:16
	global_load_dwordx4 v[18:21], v62, s[26:27]
	global_load_dwordx4 v[22:25], v[8:9], off offset:16
	global_load_dwordx4 v[26:29], v[8:9], off
	v_lshl_add_u64 v[4:5], v[4:5], 2, s[26:27]
	v_addc_co_u32_e32 v3, vcc, 0, v1, vcc
	global_load_dwordx4 v[30:33], v[6:7], off offset:16
	global_load_dwordx4 v[34:37], v[6:7], off
	global_load_dwordx4 v[38:41], v[4:5], off offset:16
	global_load_dwordx4 v[42:45], v[4:5], off
	global_load_dwordx4 v[46:49], v[2:3], off
	v_add_u32_e32 v63, v164, v162
	v_add_u32_e32 v132, v164, v165
	v_add_u32_e32 v133, v164, v166
	v_add_u32_e32 v140, v164, v167
	v_add_u32_e32 v147, 0x14000, v161
	v_add_u32_e32 v148, v169, v162
	v_add_u32_e32 v149, v169, v165
	v_add_u32_e32 v150, v169, v166
	v_add_u32_e32 v151, v169, v167
	v_add_u32_e32 v152, 16, v184
	v_readlane_b32 s20, v254, 28
	v_readfirstlane_b32 s1, v152
	s_mov_b32 m0, s1
	v_readlane_b32 s21, v254, 29
	s_mov_b32 s45, 0
	s_mov_b64 s[40:41], 0
	s_mov_b32 s46, 0
	s_waitcnt vmcnt(9)
	ds_write_b128 v161, v[10:13] offset:32768
	s_waitcnt vmcnt(8)
	v_cvt_pk_bf16_f32 v12, v14, v15
	v_cvt_pk_bf16_f32 v13, v16, v17
	s_waitcnt vmcnt(5)
	v_cvt_pk_bf16_f32 v14, v26, v27
	v_cvt_pk_bf16_f32 v15, v28, v29
	v_cvt_pk_bf16_f32 v10, v18, v19
	v_cvt_pk_bf16_f32 v11, v20, v21
	v_cvt_pk_bf16_f32 v16, v22, v23
	v_cvt_pk_bf16_f32 v17, v24, v25
	s_waitcnt vmcnt(3)
	v_cvt_pk_bf16_f32 v18, v34, v35
	v_cvt_pk_bf16_f32 v19, v36, v37
	v_cvt_pk_bf16_f32 v20, v30, v31
	v_cvt_pk_bf16_f32 v21, v32, v33
	s_waitcnt vmcnt(1)
	v_cvt_pk_bf16_f32 v22, v42, v43
	v_cvt_pk_bf16_f32 v23, v44, v45
	v_cvt_pk_bf16_f32 v24, v38, v39
	v_cvt_pk_bf16_f32 v25, v40, v41
	s_waitcnt vmcnt(0)
	ds_write_b128 v161, v[46:49] offset:40960
	ds_write_b128 v161, v[10:13]
	ds_write_b128 v161, v[14:17] offset:8192
	ds_write_b128 v161, v[18:21] offset:16384
	ds_write_b128 v161, v[22:25] offset:24576
	s_waitcnt lgkmcnt(0)
	s_barrier
	ds_read_b128 v[12:15], v63 offset:32768
	v_add_u32_e32 v10, v163, v162
	ds_read_b128 v[16:19], v10
	ds_read_b128 v[20:23], v10 offset:4096
	ds_read_b128 v[24:27], v63 offset:36864
	s_waitcnt lgkmcnt(2)
	v_mfma_f32_32x32x16_bf16 v[112:127], v[12:15], v[16:19], 0
	v_add_u32_e32 v11, v163, v165
	s_waitcnt lgkmcnt(1)
	v_mfma_f32_32x32x16_bf16 v[80:95], v[12:15], v[20:23], 0
	ds_read_b128 v[12:15], v132 offset:32768
	s_waitcnt lgkmcnt(1)
	v_mfma_f32_32x32x16_bf16 v[96:111], v[24:27], v[16:19], 0
	v_mfma_f32_32x32x16_bf16 v[64:79], v[24:27], v[20:23], 0
	ds_read_b128 v[16:19], v11
	ds_read_b128 v[20:23], v11 offset:4096
	ds_read_b128 v[24:27], v132 offset:36864
	s_waitcnt lgkmcnt(2)
	v_mfma_f32_32x32x16_bf16 v[112:127], v[12:15], v[16:19], v[112:127]
	s_waitcnt lgkmcnt(0)
	v_mfma_f32_32x32x16_bf16 v[96:111], v[24:27], v[16:19], v[96:111]
	v_mfma_f32_32x32x16_bf16 v[80:95], v[12:15], v[20:23], v[80:95]
	ds_read_b128 v[14:17], v133 offset:32768
	v_add_u32_e32 v12, v163, v166
	v_add_u32_e32 v13, v163, v167
	v_mfma_f32_32x32x16_bf16 v[64:79], v[24:27], v[20:23], v[64:79]
	ds_read_b128 v[18:21], v12
	ds_read_b128 v[22:25], v12 offset:4096
	ds_read_b128 v[26:29], v133 offset:36864
	s_waitcnt lgkmcnt(2)
	v_mfma_f32_32x32x16_bf16 v[112:127], v[14:17], v[18:21], v[112:127]
	s_waitcnt lgkmcnt(1)
	v_mfma_f32_32x32x16_bf16 v[80:95], v[14:17], v[22:25], v[80:95]
	ds_read_b128 v[14:17], v140 offset:32768
	s_waitcnt lgkmcnt(1)
	v_mfma_f32_32x32x16_bf16 v[96:111], v[26:29], v[18:21], v[96:111]
	v_mfma_f32_32x32x16_bf16 v[64:79], v[26:29], v[22:25], v[64:79]
	ds_read_b128 v[18:21], v13
	ds_read_b128 v[22:25], v13 offset:4096
	ds_read_b128 v[26:29], v140 offset:36864
	global_load_dwordx4 v[30:33], v62, s[26:27] offset:256
	global_load_dwordx4 v[34:37], v62, s[26:27] offset:272
	global_load_dwordx4 v[38:41], v[8:9], off offset:256
	global_load_dwordx4 v[42:45], v[8:9], off offset:272
	s_waitcnt lgkmcnt(2)
	v_mfma_f32_32x32x16_bf16 v[112:127], v[14:17], v[18:21], v[112:127]
	s_waitcnt lgkmcnt(0)
	v_mfma_f32_32x32x16_bf16 v[96:111], v[26:29], v[18:21], v[96:111]
	global_load_dwordx4 v[18:21], v[6:7], off offset:256
	global_load_dwordx4 v[46:49], v[6:7], off offset:272
	global_load_dwordx4 v[50:53], v[4:5], off offset:256
	global_load_dwordx4 v[54:57], v[4:5], off offset:272
	global_load_dwordx4 v[58:61], v[0:1], off offset:128
	s_waitcnt vmcnt(4)
	v_cvt_pk_bf16_f32 v18, v18, v19
	v_mfma_f32_32x32x16_bf16 v[80:95], v[14:17], v[22:25], v[80:95]
	global_load_dwordx4 v[14:17], v[2:3], off offset:128
	v_cvt_pk_bf16_f32 v19, v20, v21
	s_waitcnt vmcnt(4)
	v_cvt_pk_bf16_f32 v20, v46, v47
	v_cvt_pk_bf16_f32 v21, v48, v49
	v_mfma_f32_32x32x16_bf16 v[64:79], v[26:29], v[22:25], v[64:79]
	v_cvt_pk_bf16_f32 v22, v30, v31
	v_cvt_pk_bf16_f32 v23, v32, v33
	v_cvt_pk_bf16_f32 v24, v34, v35
	v_cvt_pk_bf16_f32 v25, v36, v37
	v_cvt_pk_bf16_f32 v26, v38, v39
	v_cvt_pk_bf16_f32 v27, v40, v41
	v_cvt_pk_bf16_f32 v28, v42, v43
	v_cvt_pk_bf16_f32 v29, v44, v45
	s_waitcnt vmcnt(3)
	v_cvt_pk_bf16_f32 v30, v50, v51
	v_cvt_pk_bf16_f32 v31, v52, v53
	s_waitcnt vmcnt(2)
	v_cvt_pk_bf16_f32 v32, v54, v55
	v_cvt_pk_bf16_f32 v33, v56, v57
	s_waitcnt vmcnt(1)
	ds_write_b128 v147, v[58:61]
	s_waitcnt vmcnt(0)
	ds_write_b128 v147, v[14:17] offset:8192
	ds_write_b128 v161, v[22:25] offset:49152
	ds_write_b128 v161, v[26:29] offset:57344
	ds_write_b128 v168, v[18:21] offset:16384
	ds_write_b128 v168, v[30:33] offset:24576
	s_waitcnt lgkmcnt(0)
	s_barrier
; #define MFMA32(a, b, c) __builtin_amdgcn_mfma_f32_32x32x16_bf16((a), (b), (c), 0, 0, 0)
; template <bool AF32, int AMODE, bool SWAP>
; DI void mainloop_rs(f32x16 (&acc)[2][2], const void* Abase, int lda, int arow0, int amax, const bf16_t* Bbase, int ldb, int brow0, int nk, int tid) {
;     ...
;     for (int kt = 0; kt < nk; ++kt) {
;         const bool more = kt + 1 < nk;
;         if (more) gload(kt + 1);
;         const char* sb = smem + (kt & 1) * G_STAGE;
; #pragma unroll
;         for (int ks = 0; ks < 4; ++ks) {
;             const int co = (lk ^ (2 * ks)) << 4;
;             bf16x8 a0 = *(const bf16x8*)(sb + a_off + co), a1 = *(const bf16x8*)(sb + a_off + 4096 + co);
;             bf16x8 b0 = *(const bf16x8*)(sb + b_off + co), b1 = *(const bf16x8*)(sb + b_off + 4096 + co);
;             if (!SWAP) { acc[0][0] = MFMA32(a0, b0, acc[0][0]); acc[0][1] = MFMA32(a0, b1, acc[0][1]); acc[1][0] = MFMA32(a1, b0, acc[1][0]); acc[1][1] = MFMA32(a1, b1, acc[1][1]); }
;             else { acc[0][0] = MFMA32(b0, a0, acc[0][0]); acc[0][1] = MFMA32(b1, a0, acc[0][1]); acc[1][0] = MFMA32(b0, a1, acc[1][0]); acc[1][1] = MFMA32(b1, a1, acc[1][1]); }
;         }
;         if (more) lstore((kt + 1) & 1);
;         __syncthreads();
	ds_read_b128 v[14:17], v148 offset:32768
	ds_read_b128 v[18:21], v10 offset:49152
	ds_read_b128 v[22:25], v10 offset:53248
	ds_read_b128 v[26:29], v148 offset:36864
	s_waitcnt lgkmcnt(2)
	v_mfma_f32_32x32x16_bf16 v[112:127], v[14:17], v[18:21], v[112:127]
	s_waitcnt lgkmcnt(1)
	v_mfma_f32_32x32x16_bf16 v[80:95], v[14:17], v[22:25], v[80:95]
	s_waitcnt lgkmcnt(0)
	v_mfma_f32_32x32x16_bf16 v[96:111], v[26:29], v[18:21], v[96:111]
	v_mfma_f32_32x32x16_bf16 v[64:79], v[26:29], v[22:25], v[64:79]
	ds_read_b128 v[14:17], v149 offset:32768
	ds_read_b128 v[18:21], v11 offset:49152
	ds_read_b128 v[22:25], v11 offset:53248
	ds_read_b128 v[26:29], v149 offset:36864
	s_waitcnt lgkmcnt(2)
	v_mfma_f32_32x32x16_bf16 v[112:127], v[14:17], v[18:21], v[112:127]
	s_waitcnt lgkmcnt(1)
	v_mfma_f32_32x32x16_bf16 v[80:95], v[14:17], v[22:25], v[80:95]
	s_waitcnt lgkmcnt(0)
	v_mfma_f32_32x32x16_bf16 v[96:111], v[26:29], v[18:21], v[96:111]
	v_mfma_f32_32x32x16_bf16 v[64:79], v[26:29], v[22:25], v[64:79]
	ds_read_b128 v[14:17], v150 offset:32768
	ds_read_b128 v[18:21], v12 offset:49152
	ds_read_b128 v[22:25], v12 offset:53248
	ds_read_b128 v[26:29], v150 offset:36864
	s_waitcnt lgkmcnt(2)
	v_mfma_f32_32x32x16_bf16 v[112:127], v[14:17], v[18:21], v[112:127]
	s_waitcnt lgkmcnt(1)
	v_mfma_f32_32x32x16_bf16 v[80:95], v[14:17], v[22:25], v[80:95]
	ds_read_b128 v[14:17], v151 offset:32768
	s_waitcnt lgkmcnt(1)
	v_mfma_f32_32x32x16_bf16 v[96:111], v[26:29], v[18:21], v[96:111]
	v_mfma_f32_32x32x16_bf16 v[64:79], v[26:29], v[22:25], v[64:79]
	global_load_dwordx4 v[18:21], v62, s[26:27] offset:512
	global_load_dwordx4 v[22:25], v62, s[26:27] offset:528
	ds_read_b128 v[26:29], v13 offset:49152
	global_load_dwordx4 v[30:33], v[8:9], off offset:528
	global_load_dwordx4 v[34:37], v[8:9], off offset:512
	ds_read_b128 v[38:41], v13 offset:53248
	ds_read_b128 v[42:45], v151 offset:36864
	global_load_dwordx4 v[46:49], v[6:7], off offset:512
	global_load_dwordx4 v[50:53], v[6:7], off offset:528
	global_load_dwordx4 v[54:57], v[4:5], off offset:512
	global_load_dwordx4 v[58:61], v[4:5], off offset:528
	global_load_dwordx4 v[128:131], v[0:1], off offset:256
	s_waitcnt lgkmcnt(2)
	v_mfma_f32_32x32x16_bf16 v[112:127], v[14:17], v[26:29], v[112:127]
	s_waitcnt lgkmcnt(0)
	v_mfma_f32_32x32x16_bf16 v[96:111], v[42:45], v[26:29], v[96:111]
	global_load_dwordx4 v[26:29], v[2:3], off offset:256
	v_mfma_f32_32x32x16_bf16 v[80:95], v[14:17], v[38:41], v[80:95]
	s_waitcnt vmcnt(9)
	v_cvt_pk_bf16_f32 v14, v18, v19
	v_mfma_f32_32x32x16_bf16 v[64:79], v[42:45], v[38:41], v[64:79]
	v_cvt_pk_bf16_f32 v15, v20, v21
	s_waitcnt vmcnt(8)
	v_cvt_pk_bf16_f32 v16, v22, v23
	v_cvt_pk_bf16_f32 v17, v24, v25
	s_waitcnt vmcnt(6)
	v_cvt_pk_bf16_f32 v18, v34, v35
	v_cvt_pk_bf16_f32 v19, v36, v37
	v_cvt_pk_bf16_f32 v20, v30, v31
	v_cvt_pk_bf16_f32 v21, v32, v33
	s_waitcnt vmcnt(5)
	v_cvt_pk_bf16_f32 v22, v46, v47
	v_cvt_pk_bf16_f32 v23, v48, v49
	s_waitcnt vmcnt(4)
	v_cvt_pk_bf16_f32 v24, v50, v51
	v_cvt_pk_bf16_f32 v25, v52, v53
	s_waitcnt vmcnt(3)
	v_cvt_pk_bf16_f32 v30, v54, v55
	v_cvt_pk_bf16_f32 v31, v56, v57
	s_waitcnt vmcnt(2)
	v_cvt_pk_bf16_f32 v32, v58, v59
	v_cvt_pk_bf16_f32 v33, v60, v61
	s_waitcnt vmcnt(1)
	ds_write_b128 v161, v[128:131] offset:32768
	s_waitcnt vmcnt(0)
	ds_write_b128 v161, v[26:29] offset:40960
	ds_write_b128 v161, v[14:17]
	ds_write_b128 v161, v[18:21] offset:8192
	ds_write_b128 v161, v[22:25] offset:16384
	ds_write_b128 v161, v[30:33] offset:24576
	s_waitcnt lgkmcnt(0)
	s_barrier
	ds_read_b128 v[14:17], v63 offset:32768
	ds_read_b128 v[18:21], v10
	ds_read_b128 v[22:25], v10 offset:4096
	ds_read_b128 v[26:29], v63 offset:36864
	s_waitcnt lgkmcnt(2)
	v_mfma_f32_32x32x16_bf16 v[112:127], v[14:17], v[18:21], v[112:127]
	v_lshlrev_b32_e32 v63, 1, v174
	s_waitcnt lgkmcnt(0)
	v_mfma_f32_32x32x16_bf16 v[96:111], v[26:29], v[18:21], v[96:111]
	v_mfma_f32_32x32x16_bf16 v[80:95], v[14:17], v[22:25], v[80:95]
	global_load_dwordx4 v[14:17], v62, s[26:27] offset:768
	global_load_dwordx4 v[18:21], v62, s[26:27] offset:784
	global_load_dwordx4 v[30:33], v[8:9], off offset:768
	global_load_dwordx4 v[34:37], v[8:9], off offset:784
	ds_read_b128 v[38:41], v132 offset:32768
	s_waitcnt vmcnt(3)
	v_cvt_pk_bf16_f32 v14, v14, v15
	v_mfma_f32_32x32x16_bf16 v[64:79], v[26:29], v[22:25], v[64:79]
	global_load_dwordx4 v[22:25], v[6:7], off offset:768
	s_nop 0
	global_load_dwordx4 v[6:9], v[6:7], off offset:784
	ds_read_b128 v[26:29], v11
	global_load_dwordx4 v[42:45], v[4:5], off offset:784
	global_load_dwordx4 v[46:49], v[4:5], off offset:768
	global_load_dwordx4 v[50:53], v[0:1], off offset:384
	ds_read_b128 v[54:57], v11 offset:4096
	ds_read_b128 v[58:61], v132 offset:36864
	global_load_dwordx4 v[0:3], v[2:3], off offset:384
	v_add_u32_e32 v4, s43, v173
	v_add_u32_e32 v5, s43, v175
	s_waitcnt lgkmcnt(2)
	v_mfma_f32_32x32x16_bf16 v[112:127], v[38:41], v[26:29], v[112:127]
	v_med3_i32 v4, v4, 0, v211
	v_med3_i32 v153, v5, 0, v211
	v_add_u32_e32 v5, s28, v181
	v_lshl_or_b32 v62, v5, 10, v174
	v_lshl_or_b32 v154, v4, 11, v63
	v_cvt_pk_bf16_f32 v15, v16, v17
	s_waitcnt vmcnt(8)
	v_cvt_pk_bf16_f32 v16, v18, v19
	s_waitcnt lgkmcnt(0)
	v_mfma_f32_32x32x16_bf16 v[96:111], v[58:61], v[26:29], v[96:111]
	v_add_u32_e32 v26, s43, v179
	v_add_u32_e32 v27, s43, v180
	v_med3_i32 v155, v26, 0, v211
	v_add_u32_e32 v26, s28, v182
	v_med3_i32 v156, v27, 0, v211
	v_lshl_or_b32 v146, v26, 10, v178
	ds_read_b128 v[26:29], v133 offset:32768
	v_mfma_f32_32x32x16_bf16 v[80:95], v[38:41], v[54:57], v[80:95]
	v_cvt_pk_bf16_f32 v17, v20, v21
	s_waitcnt vmcnt(7)
	v_cvt_pk_bf16_f32 v18, v30, v31
	v_cvt_pk_bf16_f32 v19, v32, v33
	s_waitcnt vmcnt(6)
	v_cvt_pk_bf16_f32 v20, v34, v35
	v_cvt_pk_bf16_f32 v21, v36, v37
	v_lshl_or_b32 v176, v155, 11, v63
	v_ashrrev_i32_e32 v63, 31, v62
	v_mfma_f32_32x32x16_bf16 v[64:79], v[58:61], v[54:57], v[64:79]
	ds_read_b128 v[38:41], v12
	ds_read_b128 v[54:57], v12 offset:4096
	ds_read_b128 v[58:61], v133 offset:36864
	ds_read_b128 v[128:131], v13
	ds_read_b128 v[132:135], v13 offset:4096
	ds_read_b128 v[136:139], v140 offset:32768
	ds_read_b128 v[140:143], v140 offset:36864
	s_waitcnt vmcnt(1)
	ds_write_b128 v147, v[50:53]
	s_waitcnt vmcnt(0)
	ds_write_b128 v147, v[0:3] offset:8192
	s_waitcnt lgkmcnt(8)
	v_mfma_f32_32x32x16_bf16 v[112:127], v[26:29], v[38:41], v[112:127]
	v_cvt_pk_bf16_f32 v4, v22, v23
	v_cvt_pk_bf16_f32 v5, v24, v25
	v_cvt_pk_bf16_f32 v6, v6, v7
	v_cvt_pk_bf16_f32 v7, v8, v9
	v_cvt_pk_bf16_f32 v22, v46, v47
	v_cvt_pk_bf16_f32 v23, v48, v49
	v_cvt_pk_bf16_f32 v24, v42, v43
	s_waitcnt lgkmcnt(6)
	v_mfma_f32_32x32x16_bf16 v[96:111], v[58:61], v[38:41], v[96:111]
	v_cvt_pk_bf16_f32 v25, v44, v45
	ds_write_b128 v161, v[14:17] offset:49152
	ds_write_b128 v161, v[18:21] offset:57344
	ds_write_b128 v168, v[4:7] offset:16384
	ds_write_b128 v168, v[22:25] offset:24576
	s_waitcnt lgkmcnt(0)
	s_barrier
; template <bool AF32, int AMODE, bool SWAP>
; DI void mainloop_rs(f32x16 (&acc)[2][2], const void* Abase, int lda, int arow0, int amax, const bf16_t* Bbase, int ldb, int brow0, int nk, int tid) {
;     ...
; #pragma unroll
;         for (int ks = 0; ks < 4; ++ks) {
;             const int co = (lk ^ (2 * ks)) << 4;
;             bf16x8 a0 = *(const bf16x8*)(sb + a_off + co), a1 = *(const bf16x8*)(sb + a_off + 4096 + co);
;             bf16x8 b0 = *(const bf16x8*)(sb + b_off + co), b1 = *(const bf16x8*)(sb + b_off + 4096 + co);
;             if (!SWAP) { acc[0][0] = MFMA32(a0, b0, acc[0][0]); acc[0][1] = MFMA32(a0, b1, acc[0][1]); acc[1][0] = MFMA32(a1, b0, acc[1][0]); acc[1][1] = MFMA32(a1, b1, acc[1][1]); }
;             else { acc[0][0] = MFMA32(b0, a0, acc[0][0]); acc[0][1] = MFMA32(b1, a0, acc[0][1]); acc[1][0] = MFMA32(b0, a1, acc[1][0]); acc[1][1] = MFMA32(b1, a1, acc[1][1]); }
;         }
; template <int AMODE, bool SWAP, int MI>
; DI void mainloop_dma(f32x16 (&acc)[MI][2], const TD& c, const TD& n, bool hasn, bool primed, int& s, int tid) {
;     ...
; #pragma unroll
;     for (int mi = 0; mi < MI; ++mi)
; #pragma unroll
;         for (int ni = 0; ni < 2; ++ni)
; #pragma unroll
;             for (int r = 0; r < 16; ++r) acc[mi][ni][r] = 0.f;
;     constexpr int NP = 4 + C::NBI;
;     auto offs = [&](const TD& t, int (&ao)[4], int (&bo)[C::NBI]) {
; #pragma unroll
;         for (int i = 0; i < 4; ++i) {
;             int row = t.arow0 + (4 * w + i) * 8 + (l >> 3); row = row < 0 ? 0 : (row > t.amax ? t.amax : row);
;             ao[i] = row * t.lda + ((l & 7) ^ (((l >> 4) + 4 * (i & 1)) & 7)) * 8;
;         }
; #pragma unroll
;         for (int i = 0; i < C::NBI; ++i) {
;             const int row = t.brow0 + (C::NBI * w + i) * 8 + (l >> 3);
;             bo[i] = row * t.ldb + ((l & 7) ^ (((l >> 4) + 4 * (i & 1)) & 7)) * 8;
;         }
;     };
;     auto piece = [&](const TD& t, const int (&ao)[4], const int (&bo)[C::NBI], int kt, int st, int i) {
;         char* sb = smem + st * C::STAGE;
;         if (i < 4) {
;             const int ka = (AMODE == 1) ? ((kt >> 1) * 192 + (kt & 1) * 64) : kt * 64;
;             __builtin_amdgcn_global_load_lds((const __attribute__((address_space(1))) void*)(t.A + ka + ao[i]), (__attribute__((address_space(3))) void*)(sb + (4 * w + i) * 1024), 16, 0, 0);
;         } else {
	ds_read_b128 v[0:3], v10 offset:49152
	ds_read_b128 v[4:7], v10 offset:53248
	ds_read_b128 v[14:17], v148 offset:32768
	ds_read_b128 v[18:21], v148 offset:36864
	ds_read_b128 v[22:25], v11 offset:49152
	ds_read_b128 v[8:11], v11 offset:53248
	ds_read_b128 v[30:33], v149 offset:32768
	ds_read_b128 v[34:37], v149 offset:36864
	ds_read_b128 v[38:41], v12 offset:49152
	ds_read_b128 v[48:51], v12 offset:53248
	ds_read_b128 v[44:47], v150 offset:32768
	ds_read_b128 v[192:195], v150 offset:36864
	ds_read_b128 v[196:199], v13 offset:49152
	ds_read_b128 v[200:203], v13 offset:53248
	ds_read_b128 v[204:207], v151 offset:32768
	ds_read_b128 v[222:225], v151 offset:36864
	v_lshlrev_b32_e32 v13, 1, v178
	v_mfma_f32_32x32x16_bf16 v[80:95], v[26:29], v[54:57], v[80:95]
	v_add_u32_e32 v26, 0x400, v152
	s_waitcnt lgkmcnt(0)
	v_readfirstlane_b32 s1, v26
	v_add_u32_e32 v26, 0x800, v152
	s_barrier
	s_waitcnt lgkmcnt(0)
	v_mfma_f32_32x32x16_bf16 v[112:127], v[136:139], v[128:131], v[112:127]
	s_barrier
	global_load_lds_dwordx4 v154, s[20:21]
	v_lshl_or_b32 v12, v153, 11, v13
	s_mov_b32 m0, s1
	v_readfirstlane_b32 s1, v26
	v_lshl_or_b32 v26, v156, 11, v13
	v_mfma_f32_32x32x16_bf16 v[96:111], v[140:143], v[128:131], v[96:111]
	v_add_u32_e32 v13, 0xc00, v152
	global_load_lds_dwordx4 v12, s[20:21]
	s_mov_b32 m0, s1
	v_readfirstlane_b32 s1, v13
	v_add_u32_e32 v13, 16, v183
	v_add_u32_e32 v27, 0x8000, v13
	global_load_lds_dwordx4 v176, s[20:21]
	s_mov_b32 m0, s1
	v_readfirstlane_b32 s1, v27
	v_add_u32_e32 v13, 0x8400, v13
	global_load_lds_dwordx4 v26, s[20:21]
	v_lshl_add_u64 v[28:29], v[62:63], 1, s[18:19]
	s_mov_b32 m0, s1
	v_ashrrev_i32_e32 v147, 31, v146
	v_readfirstlane_b32 s1, v13
	v_add_u32_e32 v13, 0xc000, v152
	global_load_lds_dwordx4 v[28:29], off
	v_lshl_add_u64 v[42:43], v[146:147], 1, s[18:19]
	s_mov_b32 m0, s1
	v_readfirstlane_b32 s1, v13
	v_readlane_b32 s20, v254, 52
	v_add_u32_e32 v13, 0xc400, v152
	global_load_lds_dwordx4 v[42:43], off
	s_mov_b32 m0, s1
	v_readlane_b32 s21, v254, 53
	v_readfirstlane_b32 s1, v13
	v_add_u32_e32 v13, 0xc800, v152
	v_mfma_f32_32x32x16_bf16 v[112:127], v[14:17], v[0:3], v[112:127]
	v_mov_b32_e32 v27, v177
	v_mov_b32_e32 v155, v177
	global_load_lds_dwordx4 v154, s[20:21]
	s_mov_b32 m0, s1
	v_readfirstlane_b32 s1, v13
	v_add_u32_e32 v13, 0xcc00, v152
	v_mfma_f32_32x32x16_bf16 v[96:111], v[18:21], v[0:3], v[96:111]
	v_add_u32_e32 v2, s52, v183
	global_load_lds_dwordx4 v12, s[20:21]
	s_mov_b32 m0, s1
	v_readfirstlane_b32 s1, v13
	v_add_u32_e32 v3, 0x1000, v2
	global_load_lds_dwordx4 v176, s[20:21]
	s_mov_b32 m0, s1
	v_readfirstlane_b32 s1, v3
	v_add_u32_e32 v2, 0x1400, v2
	global_load_lds_dwordx4 v26, s[20:21]
	v_lshl_add_u64 v[0:1], v[28:29], 0, s[94:95]
	s_mov_b32 m0, s1
	v_readfirstlane_b32 s1, v2
	global_load_lds_dwordx4 v[0:1], off
	v_lshl_add_u64 v[0:1], v[42:43], 0, s[94:95]
	s_mov_b32 m0, s1
	v_mfma_f32_32x32x16_bf16 v[64:79], v[58:61], v[54:57], v[64:79]
	global_load_lds_dwordx4 v[0:1], off
	v_lshl_add_u32 v0, s42, 17, v190
	s_lshl_b32 s1, s0, 20
	v_subrev_u32_e32 v0, s1, v0
	v_ashrrev_i32_e32 v1, 31, v0
	v_lshl_add_u64 v[146:147], v[0:1], 1, s[48:49]
	v_mfma_f32_32x32x16_bf16 v[80:95], v[136:139], v[132:135], v[80:95]
	v_lshl_add_u32 v0, s42, 7, v181
	s_lshl_b32 s0, s0, 10
	v_subrev_u32_e32 v0, s0, v0
	v_lshl_or_b32 v0, v0, 10, v174
	v_ashrrev_i32_e32 v1, 31, v0
	v_lshl_add_u64 v[148:149], v[0:1], 1, s[48:49]
	v_mov_b32_e32 v13, v177
	v_mfma_f32_32x32x16_bf16 v[64:79], v[140:143], v[132:135], v[64:79]
	v_mov_b32_e32 v0, 0
	v_lshl_add_u64 v[150:151], s[50:51], 0, v[176:177]
	v_lshl_add_u64 v[152:153], s[50:51], 0, v[26:27]
	v_lshl_add_u64 v[154:155], s[50:51], 0, v[154:155]
	v_lshl_add_u64 v[156:157], s[50:51], 0, v[12:13]
	v_mov_b32_e32 v1, v0
	v_mov_b32_e32 v2, v0
	v_mfma_f32_32x32x16_bf16 v[80:95], v[14:17], v[4:7], v[80:95]
	v_mov_b32_e32 v3, v0
	v_mov_b32_e32 v12, v0
	v_mov_b32_e32 v13, v0
	v_mov_b32_e32 v14, v0
	v_mov_b32_e32 v15, v0
	v_mov_b32_e32 v42, v0
	v_mov_b32_e32 v43, v0
	v_mfma_f32_32x32x16_bf16 v[64:79], v[18:21], v[4:7], v[64:79]
	v_mov_b32_e32 v4, v0
	v_mov_b32_e32 v5, v0
	v_mov_b32_e32 v6, v0
	v_mov_b32_e32 v7, v0
	v_mov_b32_e32 v16, v0
	v_mov_b32_e32 v17, v0
	v_mov_b32_e32 v18, v0
	v_mfma_f32_32x32x16_bf16 v[112:127], v[30:33], v[22:25], v[112:127]
	v_mov_b32_e32 v19, v0
	v_mov_b32_e32 v20, v0
	v_mov_b32_e32 v21, v0
	v_mov_b32_e32 v26, v0
	v_mov_b32_e32 v27, v0
	v_mov_b32_e32 v28, v0
	v_mov_b32_e32 v29, v0
	v_mfma_f32_32x32x16_bf16 v[96:111], v[34:37], v[22:25], v[96:111]
	v_mov_b32_e32 v22, v0
	v_mov_b32_e32 v23, v0
	v_mov_b32_e32 v24, v0
	v_mov_b32_e32 v25, v0
	v_mov_b32_e32 v52, v0
	v_mov_b32_e32 v53, v0
	v_mov_b32_e32 v54, v0
	v_mfma_f32_32x32x16_bf16 v[80:95], v[30:33], v[8:11], v[80:95]
	v_mov_b32_e32 v32, v0
	v_mov_b32_e32 v33, v0
	v_mov_b32_e32 v30, v0
	v_mov_b32_e32 v31, v0
	v_mov_b32_e32 v55, v0
	v_mov_b32_e32 v56, v0
	v_mov_b32_e32 v57, v0
	v_mfma_f32_32x32x16_bf16 v[64:79], v[34:37], v[8:11], v[64:79]
	v_mov_b32_e32 v8, v0
	v_mov_b32_e32 v9, v0
	v_mov_b32_e32 v10, v0
	v_mov_b32_e32 v11, v0
	v_mov_b32_e32 v34, v0
	v_mov_b32_e32 v35, v0
	v_mov_b32_e32 v36, v0
	v_mfma_f32_32x32x16_bf16 v[112:127], v[44:47], v[38:41], v[112:127]
	v_mov_b32_e32 v37, v0
	v_mov_b32_e32 v58, v0
	v_mov_b32_e32 v59, v0
	v_mov_b32_e32 v60, v0
	v_mov_b32_e32 v61, v0
	v_mov_b32_e32 v62, v0
	v_mov_b32_e32 v63, v0
	v_mfma_f32_32x32x16_bf16 v[96:111], v[192:195], v[38:41], v[96:111]
	v_mov_b32_e32 v38, v0
	v_mov_b32_e32 v39, v0
	v_mov_b32_e32 v40, v0
	v_mov_b32_e32 v41, v0
	v_mfma_f32_32x32x16_bf16 v[80:95], v[44:47], v[48:51], v[80:95]
	v_mov_b32_e32 v44, v0
	v_mov_b32_e32 v45, v0
	v_mov_b32_e32 v46, v0
	v_mov_b32_e32 v47, v0
	v_mfma_f32_32x32x16_bf16 v[64:79], v[192:195], v[48:51], v[64:79]
	v_mov_b32_e32 v48, v0
	v_mov_b32_e32 v49, v0
	v_mov_b32_e32 v50, v0
	v_mov_b32_e32 v51, v0
	v_mfma_f32_32x32x16_bf16 v[112:127], v[204:207], v[196:199], v[112:127]
	v_mfma_f32_32x32x16_bf16 v[96:111], v[222:225], v[196:199], v[96:111]
	v_mfma_f32_32x32x16_bf16 v[80:95], v[204:207], v[200:203], v[80:95]
	v_mfma_f32_32x32x16_bf16 v[64:79], v[222:225], v[200:203], v[64:79]
	s_branch .LBB0_1907
